# NSA unit: win-branch tiles 0/1 and slc tile 0 prefetched before the selection; q rotation VALU moved ahead of the tile waits
# baseline (speedup 1.0000x reference)
; DI unsigned cvtpk(float lo, float hi) { f32x2_t v = {lo, hi}; bf16x2_t b = __builtin_convertvector(v, bf16x2_t); return __builtin_bit_cast(unsigned, b); }
; #define MFMA32(a, b, c) __builtin_amdgcn_mfma_f32_32x32x16_bf16((a), (b), (c), 0, 0, 0)
; #define SBAR() __builtin_amdgcn_sched_barrier(0)
; template <int VSTR, int NDVB> DI void pv64(f32x16 (&O)[NDVB], const lds8* vp, const bf16x8 (&P)[4]) {
;   bf16x8 f[2][NDVB];
; #pragma unroll
;   for (int d = 0; d < NDVB; ++d) { const s16x4 lo = trrd(vp + d * 64), hi = trrd(vp + 8 * VSTR + d * 64); f[0][d] = __builtin_shufflevector(lo, hi, 0, 1, 2, 3, 4, 5, 6, 7); }
; #pragma unroll
;   for (int kk = 0; kk < 4; ++kk) {
;     if (kk < 3) {
; #pragma unroll
;       for (int d = 0; d < NDVB; ++d) { const s16x4 lo = trrd(vp + (16 * (kk + 1)) * VSTR + d * 64), hi = trrd(vp + (16 * (kk + 1) + 8) * VSTR + d * 64);
;         f[(kk + 1) & 1][d] = __builtin_shufflevector(lo, hi, 0, 1, 2, 3, 4, 5, 6, 7); }
;     }
;     SBAR();
;     __builtin_amdgcn_s_setprio(1);
; #pragma unroll
;     for (int d = 0; d < NDVB; ++d) O[d] = MFMA32(f[kk & 1][d], P[kk], O[d]);
;     __builtin_amdgcn_s_setprio(0);
;     SBAR();
;   }
; }
; template <int NDVB, bool HAS_NEXT> DI void softmax_def(f32x16& sa0, f32x16& sa1, f32x16& sb0, f32x16& sb1, f32x16 (&O)[NDVB], float& muse, float& l, bool first, bf16x8 (&P)[4], bool check = true) {
;     ...
;   float sum = 0.f;
; #pragma unroll
;   for (int i = 0; i < 16; ++i) { sa0[i] = __builtin_amdgcn_exp2f(sa0[i]); sum += sa0[i]; }
; #pragma unroll
;   for (int i = 0; i < 16; ++i) { sa1[i] = __builtin_amdgcn_exp2f(sa1[i]); sum += sa1[i]; }
;   l += sum;
;   u32x4 w;
;   w.x = cvtpk(sa0[0], sa0[1]); w.y = cvtpk(sa0[2], sa0[3]); w.z = cvtpk(sa0[4], sa0[5]); w.w = cvtpk(sa0[6], sa0[7]); P[0] = __builtin_bit_cast(bf16x8, w);
;   w.x = cvtpk(sa0[8], sa0[9]); w.y = cvtpk(sa0[10], sa0[11]); w.z = cvtpk(sa0[12], sa0[13]); w.w = cvtpk(sa0[14], sa0[15]); P[1] = __builtin_bit_cast(bf16x8, w);
;   w.x = cvtpk(sa1[0], sa1[1]); w.y = cvtpk(sa1[2], sa1[3]); w.z = cvtpk(sa1[4], sa1[5]); w.w = cvtpk(sa1[6], sa1[7]); P[2] = __builtin_bit_cast(bf16x8, w);
;   w.x = cvtpk(sa1[8], sa1[9]); w.y = cvtpk(sa1[10], sa1[11]); w.z = cvtpk(sa1[12], sa1[13]); w.w = cvtpk(sa1[14], sa1[15]); P[3] = __builtin_bit_cast(bf16x8, w);
.LBB0_903:
	v_lshlrev_b32_e32 v217, 3, v55
	v_add_f32_e32 v0, v97, v98
	v_add_f32_e32 v55, v99, v56
	v_add_f32_e32 v121, v0, v55
	v_add_f32_e32 v0, v109, v110
	v_add_f32_e32 v55, v111, v60
	v_add_f32_e32 v97, v0, v55
	v_add_f32_e32 v0, v100, v101
	v_add_f32_e32 v55, v102, v57
	v_add_f32_e32 v101, v0, v55
	v_add_f32_e32 v0, v112, v113
	v_add_f32_e32 v55, v114, v61
	v_add_f32_e32 v98, v0, v55
	v_add_f32_e32 v0, v103, v104
	v_add_f32_e32 v55, v105, v58
	v_exp_f32_e32 v50, v50
	v_add_f32_e32 v100, v0, v55
	v_add_f32_e32 v0, v115, v116
	v_add_f32_e32 v55, v117, v62
	v_exp_f32_e32 v51, v51
	v_add_f32_e32 v55, v0, v55
	v_add_f32_e32 v0, v106, v107
	v_add_f32_e32 v99, v108, v59
	v_exp_f32_e32 v103, v18
	v_add_f32_e32 v99, v0, v99
	v_add_f32_e32 v0, v118, v119
	v_add_f32_e32 v102, v120, v63
	v_exp_f32_e32 v18, v19
	v_add_f32_e32 v0, v0, v102
	v_add_f32_e32 v102, 0, v50
	v_add_f32_e32 v102, v51, v102
	v_add_f32_e32 v102, v103, v102
	v_add_f32_e32 v19, v18, v102
	v_exp_f32_e32 v102, v20
	v_exp_f32_e32 v21, v21
	v_exp_f32_e32 v22, v22
	v_exp_f32_e32 v104, v2
	v_add_f32_e32 v19, v102, v19
	v_add_f32_e32 v19, v21, v19
	v_add_f32_e32 v20, v22, v19
	v_exp_f32_e32 v19, v23
	v_exp_f32_e32 v23, v24
	v_exp_f32_e32 v24, v25
	v_exp_f32_e32 v25, v26
	v_add_f32_e32 v20, v19, v20
	v_add_f32_e32 v20, v23, v20
	v_add_f32_e32 v20, v24, v20
	v_add_f32_e32 v26, v25, v20
	v_exp_f32_e32 v20, v27
	v_exp_f32_e32 v27, v28
	v_exp_f32_e32 v28, v29
	v_exp_f32_e32 v29, v30
	v_add_f32_e32 v26, v20, v26
	v_exp_f32_e32 v30, v31
	v_add_f32_e32 v26, v27, v26
	v_exp_f32_e32 v31, v16
	v_add_f32_e32 v26, v28, v26
	v_add_f32_e32 v26, v29, v26
	v_add_f32_e32 v26, v30, v26
	v_add_f32_e32 v16, v31, v26
	v_exp_f32_e32 v26, v17
	v_exp_f32_e32 v110, v3
	v_exp_f32_e32 v105, v4
	v_exp_f32_e32 v106, v5
	v_add_f32_e32 v16, v26, v16
	v_add_f32_e32 v2, v104, v16
	v_exp_f32_e32 v107, v6
	v_add_f32_e32 v2, v110, v2
	v_exp_f32_e32 v111, v7
	v_add_f32_e32 v2, v105, v2
	v_exp_f32_e32 v108, v8
	v_add_f32_e32 v2, v106, v2
	v_exp_f32_e32 v109, v9
	v_add_f32_e32 v2, v107, v2
	v_exp_f32_e32 v112, v10
	v_add_f32_e32 v2, v111, v2
	v_exp_f32_e32 v113, v11
	v_add_f32_e32 v2, v108, v2
	v_exp_f32_e32 v114, v12
	v_add_f32_e32 v2, v109, v2
	v_exp_f32_e32 v115, v13
	v_add_f32_e32 v2, v112, v2
	v_exp_f32_e32 v116, v14
	v_add_f32_e32 v2, v113, v2
	v_exp_f32_e32 v117, v15
	v_add_f32_e32 v2, v114, v2
	v_add_f32_e32 v2, v115, v2
	v_add_f32_e32 v2, v116, v2
	v_add_f32_e32 v2, v117, v2
	v_cvt_pk_bf16_f32 v4, v102, v21
	v_cvt_pk_bf16_f32 v5, v22, v19
	v_cvt_pk_bf16_f32 v10, v31, v26
	v_add_f32_e32 v26, v26, v31
	v_add_f32_e32 v31, v110, v104
	v_add_f32_e32 v21, v21, v102
	v_add_f32_e32 v22, v19, v22
	v_add_f32_e32 v48, v48, v2
	v_cvt_pk_bf16_f32 v2, v50, v51
	v_add_f32_e32 v50, v51, v50
	v_add_f32_e32 v51, v18, v103
	v_add_f32_e32 v31, v31, v26
	v_add_f32_e32 v21, v22, v21
	v_add_f32_e32 v22, v106, v105
	v_add_f32_e32 v26, v111, v107
	v_cvt_pk_bf16_f32 v6, v23, v24
	v_add_f32_e32 v50, v51, v50
	v_add_f32_e32 v51, v26, v22
	v_add_f32_e32 v22, v24, v23
	v_add_f32_e32 v23, v20, v25
	v_add_f32_e32 v118, v23, v22
	v_add_f32_e32 v22, v109, v108
	v_add_f32_e32 v23, v113, v112
	v_cvt_pk_bf16_f32 v15, v112, v113
	v_add_f32_e32 v112, v23, v22
	v_add_f32_e32 v22, v28, v27
	v_add_f32_e32 v23, v30, v29
	v_add_f32_e32 v119, v23, v22
	v_add_f32_e32 v22, v115, v114
	v_add_f32_e32 v23, v117, v116
	v_cvt_pk_bf16_f32 v3, v103, v18
	v_cvt_pk_bf16_f32 v7, v25, v20
	v_cvt_pk_bf16_f32 v8, v27, v28
	v_cvt_pk_bf16_f32 v9, v29, v30
	v_cvt_pk_bf16_f32 v11, v104, v110
	v_cvt_pk_bf16_f32 v12, v105, v106
	v_cvt_pk_bf16_f32 v13, v107, v111
	v_cvt_pk_bf16_f32 v14, v108, v109
	v_cvt_pk_bf16_f32 v16, v114, v115
	v_add_f32_e32 v114, v23, v22
	ds_read_b64_tr_b16 v[22:23], v96 offset:27648
	ds_read_b64_tr_b16 v[24:25], v96 offset:28800
	ds_read_b64_tr_b16 v[26:27], v96 offset:27712
	ds_read_b64_tr_b16 v[28:29], v96 offset:28864
	ds_read_b64_tr_b16 v[102:103], v96 offset:29952
	ds_read_b64_tr_b16 v[104:105], v96 offset:31104
	ds_read_b64_tr_b16 v[106:107], v96 offset:30016
	ds_read_b64_tr_b16 v[108:109], v96 offset:31168
	v_cvt_pk_bf16_f32 v17, v116, v117
	s_setprio 1
	s_waitcnt lgkmcnt(6)
	v_mfma_f32_32x32x16_bf16 v[80:95], v[22:25], v[2:5], v[80:95]
	s_waitcnt lgkmcnt(4)
	v_mfma_f32_32x32x16_bf16 v[64:79], v[26:29], v[2:5], v[64:79]
	s_setprio 0
	ds_read_b64_tr_b16 v[2:3], v96 offset:32256
	ds_read_b64_tr_b16 v[4:5], v96 offset:33408
	ds_read_b64_tr_b16 v[22:23], v96 offset:32320
	ds_read_b64_tr_b16 v[24:25], v96 offset:33472
	s_setprio 1
	s_waitcnt lgkmcnt(6)
	v_mfma_f32_32x32x16_bf16 v[80:95], v[102:105], v[6:9], v[80:95]
	s_waitcnt lgkmcnt(4)
	v_mfma_f32_32x32x16_bf16 v[64:79], v[106:109], v[6:9], v[64:79]
	s_setprio 0
	ds_read_b64_tr_b16 v[6:7], v96 offset:34560
	ds_read_b64_tr_b16 v[8:9], v96 offset:35712
	ds_read_b64_tr_b16 v[28:29], v96 offset:35776
	ds_read_b64_tr_b16 v[26:27], v96 offset:34624
	s_setprio 1
	s_waitcnt lgkmcnt(6)
	v_mfma_f32_32x32x16_bf16 v[80:95], v[2:5], v[10:13], v[80:95]
	s_waitcnt lgkmcnt(4)
	v_mfma_f32_32x32x16_bf16 v[64:79], v[22:25], v[10:13], v[64:79]
	s_setprio 0
	s_setprio 1
	s_waitcnt lgkmcnt(2)
	v_mfma_f32_32x32x16_bf16 v[80:95], v[6:9], v[14:17], v[80:95]
	s_waitcnt lgkmcnt(0)
	v_mfma_f32_32x32x16_bf16 v[64:79], v[26:29], v[14:17], v[64:79]
	s_setprio 0
	ds_bpermute_b32 v2, v193, v48
	v_readlane_b32 s1, v255, 39
	s_waitcnt lgkmcnt(0)
	s_barrier
; #define LAS __attribute__((address_space(3)))
; DI void nsa_unit(const Params& p, lds8* lds, int bl, int g, int qb32) {
;     ...
;   const float lt0 = l + __shfl_xor(l, 32); const float inv0 = lt0 > 0.f ? 1.f / lt0 : 0.f;
;   { const float f = g0 * inv0;
; #pragma unroll
;     for (int d = 0; d < 2; ++d)
; #pragma unroll
;       for (int i = 0; i < 16; ++i) OT[d][i] = O[d][i] * f; }
;   { LAS float* impw = (LAS float*)(lds + NS_IMPW) + (wid * 32 + r) * 33;
;     float carry = 0.f;
; #pragma unroll
;     for (int kt = 0; kt < 2; ++kt) {
;       const float scale = __builtin_amdgcn_exp2f(cap.mrec[kt] - m) * inv0;
; #pragma unroll
;       for (int kb = 0; kb < 2; ++kb)
; #pragma unroll
;         for (int ii = 0; ii < 4; ++ii) {
;           const float qsum = cap.qs[kt][kb * 4 + ii] * scale, last = cap.ls[kt][kb * 4 + ii] * scale;
;           const float other = __shfl_xor(last, 32);
;           const int ub = 16 * kt + 8 * kb + 2 * ii;
;           const float val = qsum + (h ? other : carry);
;           carry = other;
;           impw[ub + h] = val;
;         }
;     }
;   }
;   __syncthreads();
; #pragma unroll
;   for (int ks = 0; ks < 2; ++ks) {
;     const float* rc = rope + qpos * 32 + 16 * ks + 8 * h;
;     const f32x4 c0 = *(const f32x4*)rc, c1 = *(const f32x4*)(rc + 4), s0 = *(const f32x4*)(rc + 65536), s1 = *(const f32x4*)(rc + 65536 + 4);
	v_add_f32_e32 v2, v48, v2
	v_div_scale_f32 v3, s[8:9], v2, v2, 1.0
	v_rcp_f32_e32 v4, v3
	v_div_scale_f32 v5, vcc, 1.0, v2, 1.0
	v_readlane_b32 s8, v254, 63
	v_fma_f32 v6, -v3, v4, 1.0
	v_fmac_f32_e32 v4, v6, v4
	v_mul_f32_e32 v6, v5, v4
	v_fma_f32 v7, -v3, v6, v5
	v_fmac_f32_e32 v6, v7, v4
	v_fma_f32 v3, -v3, v6, v5
	v_div_fmas_f32 v3, v3, v4, v6
	v_sub_f32_e32 v4, v49, v1
	v_exp_f32_e32 v4, v4
	v_div_fixup_f32 v3, v3, v2, 1.0
	v_cmp_lt_f32_e32 vcc, 0, v2
	v_lshl_or_b32 v2, s1, 5, v52
	v_mul_lo_u32 v2, v2, s94
	v_cndmask_b32_e32 v218, 0, v3, vcc
	v_mul_f32_e32 v3, v4, v218
	v_mul_f32_e32 v4, v56, v3
	v_mul_f32_e32 v5, v57, v3
	ds_bpermute_b32 v4, v193, v4
	ds_bpermute_b32 v5, v193, v5
	v_mul_f32_e32 v7, v58, v3
	v_mul_f32_e32 v8, v59, v3
	ds_bpermute_b32 v7, v193, v7
	ds_bpermute_b32 v8, v193, v8
	v_cmp_gt_u32_e32 vcc, 32, v199
	v_add3_u32 v2, 0, v2, v214
	v_add_u32_e32 v2, 0xd800, v2
	s_waitcnt lgkmcnt(3)
	v_cndmask_b32_e64 v6, v4, 0, vcc
	s_waitcnt lgkmcnt(2)
	v_cndmask_b32_e32 v4, v5, v4, vcc
	v_fmac_f32_e32 v6, v121, v3
	v_fmac_f32_e32 v4, v101, v3
	ds_write2_b32 v2, v6, v4 offset1:2
	s_waitcnt lgkmcnt(2)
	v_cndmask_b32_e32 v4, v7, v5, vcc
	s_waitcnt lgkmcnt(1)
	v_cndmask_b32_e32 v5, v8, v7, vcc
	v_mul_f32_e32 v6, v60, v3
	v_mul_f32_e32 v7, v61, v3
	ds_bpermute_b32 v6, v193, v6
	ds_bpermute_b32 v7, v193, v7
	v_fmac_f32_e32 v4, v100, v3
	v_fmac_f32_e32 v5, v99, v3
	ds_write2_b32 v2, v4, v5 offset0:4 offset1:6
	s_waitcnt lgkmcnt(2)
	v_cndmask_b32_e32 v4, v6, v8, vcc
	s_waitcnt lgkmcnt(1)
	v_cndmask_b32_e32 v5, v7, v6, vcc
	v_fmac_f32_e32 v4, v97, v3
	v_fmac_f32_e32 v5, v98, v3
	ds_write2_b32 v2, v4, v5 offset0:8 offset1:10
	v_mul_f32_e32 v4, v62, v3
	v_sub_f32_e32 v1, v1, v1
	ds_bpermute_b32 v4, v193, v4
	v_exp_f32_e32 v1, v1
	v_mul_f32_e32 v5, v63, v3
	ds_bpermute_b32 v5, v193, v5
	v_lshlrev_b32_e32 v186, 5, v211
	v_mul_f32_e32 v1, v1, v218
	s_waitcnt lgkmcnt(1)
	v_cndmask_b32_e32 v6, v4, v7, vcc
	v_mul_f32_e32 v7, v18, v1
	ds_bpermute_b32 v7, v193, v7
	s_waitcnt lgkmcnt(1)
	v_cndmask_b32_e32 v4, v5, v4, vcc
	v_mul_f32_e32 v8, v19, v1
	v_fmac_f32_e32 v6, v55, v3
	ds_bpermute_b32 v8, v193, v8
	v_fmac_f32_e32 v4, v0, v3
	ds_write2_b32 v2, v6, v4 offset0:12 offset1:14
	s_waitcnt lgkmcnt(2)
	v_cndmask_b32_e32 v0, v7, v5, vcc
	v_mul_f32_e32 v4, v20, v1
	v_mul_f32_e32 v5, v30, v1
	ds_bpermute_b32 v4, v193, v4
	ds_bpermute_b32 v5, v193, v5
	s_waitcnt lgkmcnt(3)
	v_cndmask_b32_e32 v3, v8, v7, vcc
	v_fmac_f32_e32 v0, v50, v1
	v_fmac_f32_e32 v3, v21, v1
	ds_write2_b32 v2, v0, v3 offset0:16 offset1:18
	s_waitcnt lgkmcnt(2)
	v_cndmask_b32_e32 v0, v4, v8, vcc
	s_waitcnt lgkmcnt(1)
	v_cndmask_b32_e32 v3, v5, v4, vcc
	v_mul_f32_e32 v4, v110, v1
	v_mul_f32_e32 v6, v111, v1
	ds_bpermute_b32 v4, v193, v4
	ds_bpermute_b32 v6, v193, v6
	v_fmac_f32_e32 v0, v118, v1
	v_fmac_f32_e32 v3, v119, v1
	ds_write2_b32 v2, v0, v3 offset0:20 offset1:22
	s_waitcnt lgkmcnt(2)
	v_cndmask_b32_e32 v0, v4, v5, vcc
	s_waitcnt lgkmcnt(1)
	v_cndmask_b32_e32 v3, v6, v4, vcc
	v_mul_f32_e32 v4, v113, v1
	v_mul_f32_e32 v5, v117, v1
	ds_bpermute_b32 v4, v193, v4
	ds_bpermute_b32 v5, v193, v5
	v_fmac_f32_e32 v0, v31, v1
	v_fmac_f32_e32 v3, v51, v1
	ds_write2_b32 v2, v0, v3 offset0:24 offset1:26
	s_waitcnt lgkmcnt(2)
	v_cndmask_b32_e32 v0, v4, v6, vcc
	s_waitcnt lgkmcnt(1)
	v_cndmask_b32_e32 v3, v5, v4, vcc
	v_fmac_f32_e32 v0, v112, v1
	v_fmac_f32_e32 v3, v114, v1
	v_readlane_b32 s9, v253, 0
	ds_write2_b32 v2, v0, v3 offset0:28 offset1:30
	s_waitcnt lgkmcnt(0)
	v_lshl_add_u64 v[0:1], v[186:187], 2, s[8:9]
	v_lshlrev_b32_e32 v186, 2, v217
	v_lshl_add_u64 v[4:5], v[0:1], 0, v[186:187]
	s_mov_b64 s[8:9], 0x40000
	v_add_co_u32_e32 v6, vcc, 0x40000, v4
	v_lshl_add_u64 v[0:1], v[4:5], 0, s[8:9]
	s_nop 0
	v_addc_co_u32_e32 v7, vcc, 0, v5, vcc
	s_barrier
	global_load_dwordx4 v[16:19], v[4:5], off offset:16
	global_load_dwordx4 v[24:27], v[4:5], off
	global_load_dwordx4 v[28:31], v[6:7], off
	global_load_dwordx4 v[20:23], v[0:1], off offset:16
	s_nop 0
	global_load_dwordx4 v[0:3], v[4:5], off offset:80
	global_load_dwordx4 v[8:11], v[4:5], off offset:64
	s_mov_b64 s[8:9], 0x40040
	v_lshl_add_u64 v[4:5], v[4:5], 0, s[8:9]
	global_load_dwordx4 v[12:15], v[6:7], off offset:64
	s_nop 0
	global_load_dwordx4 v[4:7], v[4:5], off offset:16
	s_lshl_b32 s10, s71, 20
	v_readlane_b32 s1, v254, 53
	s_add_u32 s11, s1, s10
	v_readlane_b32 s1, v254, 54
	s_addc_u32 s12, s1, 0
	s_lshl_b32 s13, s70, 7
	s_add_u32 s78, s11, s13
	s_addc_u32 s79, s12, 0
	v_readlane_b32 s1, v254, 59
	s_add_u32 s10, s1, s10
	v_readlane_b32 s1, v254, 60
	s_addc_u32 s11, s1, 0
	s_add_u32 s80, s10, s13
	s_addc_u32 s81, s11, 0
	s_lshr_b32 s6, s3, 1
	s_add_i32 s6, s6, -8
	s_max_i32 s6, s6, 0
	v_lshl_add_u32 v250, s6, 6, v212
	v_lshlrev_b32_e32 v250, 9, v250
	v_add_u32_e32 v250, v250, v192
	v_add_u32_e32 v251, 0x8000, v250
	v_lshl_add_u32 v132, v212, 9, v192
	global_load_dwordx4 v[236:239], v250, s[78:79] offset:256
	global_load_dwordx4 v[240:243], v250, s[80:81] offset:256
	global_load_dwordx4 v[244:247], v251, s[78:79] offset:256
	global_load_dwordx4 v[248:251], v251, s[80:81] offset:256
	global_load_dwordx4 v[128:131], v132, s[78:79]
	global_load_dwordx4 v[132:135], v132, s[80:81]
	v_cmp_eq_u32_e32 vcc, 0, v136
	s_and_saveexec_b64 s[8:9], vcc
	s_cbranch_execz .LBB0_905
	v_readlane_b32 s1, v255, 10
	s_nop 1
	v_mov_b32_e32 v48, s1
	ds_write_b32 v48, v187

; DI unsigned cvtpk(float lo, float hi) { f32x2_t v = {lo, hi}; bf16x2_t b = __builtin_convertvector(v, bf16x2_t); return __builtin_bit_cast(unsigned, b); }
; DI float bf2f(unsigned short u) { return __uint_as_float(((unsigned)u) << 16); }
; #define NS_GLOAD(k_, KR, VR) do { const int jj = __builtin_amdgcn_readfirstlane(jl[(k_)]); KR = *(const u32x4*)(kg + (size_t)(64 * jj + sr) * pitch + sc * 8); VR = *(const u32x4*)(vg + (size_t)(64 * jj + sr) * pitch + sc * 8); } while (0)
; #define NS_LSTORE(st_, KR, VR) do { lds8* b = lds + (st_) * NS_STAGE; *(LAS u32x4*)(b + sr * NS_STR + sc * 16) = KR; *(LAS u32x4*)(b + 64 * NS_STR + sr * NS_STR + sc * 16) = VR; } while (0)
; template <int MODE>
; DI void nsa_branch(lds8* lds, const bf16_t* kg, const bf16_t* vg, int pitch, unsigned tiles, const bf16x8 (&q)[4], int qpos, unsigned mybits, int blk,
;                    f32x16 (&O)[2], float& muse, float& l, int tid, int lane, int grp, CmpCap& cap) {
;     ...
;   NS_GLOAD(0, kra, vra); NS_LSTORE(0, kra, vra);
;   if (ntl > 1) { NS_GLOAD(1, kra, vra); NS_LSTORE(1, kra, vra); }
;   __syncthreads();
; DI void nsa_unit(const Params& p, lds8* lds, int bl, int g, int qb32) {
;     ...
; #pragma unroll
;   for (int ks = 0; ks < 2; ++ks) {
;     const float* rc = rope + qpos * 32 + 16 * ks + 8 * h;
;     const f32x4 c0 = *(const f32x4*)rc, c1 = *(const f32x4*)(rc + 4), s0 = *(const f32x4*)(rc + 65536), s1 = *(const f32x4*)(rc + 65536 + 4);
;     float o1[8], o2[8];
; #pragma unroll
;     for (int e = 0; e < 8; ++e) { const float x1 = bf2f((unsigned short)qraw[ks][e]), x2 = bf2f((unsigned short)qraw[ks + 2][e]); const float cc = e < 4 ? c0[e & 3] : c1[e & 3], sn = e < 4 ? s0[e & 3] : s1[e & 3];
;       o1[e] = x1 * cc - x2 * sn; o2[e] = x2 * cc + x1 * sn; }
;     u32x4 w; w.x = cvtpk(o1[0], o1[1]); w.y = cvtpk(o1[2], o1[3]); w.z = cvtpk(o1[4], o1[5]); w.w = cvtpk(o1[6], o1[7]); qrot[ks] = __builtin_bit_cast(bf16x8, w);
;     w.x = cvtpk(o2[0], o2[1]); w.y = cvtpk(o2[2], o2[3]); w.z = cvtpk(o2[4], o2[5]); w.w = cvtpk(o2[6], o2[7]); qrot[ks + 2] = __builtin_bit_cast(bf16x8, w);
;   }
.LBB0_932:
	s_or_b64 exec, exec, s[10:11]
	s_lshl_b32 s10, s71, 20
	v_readlane_b32 s1, v254, 53
	s_add_u32 s11, s1, s10
	v_readlane_b32 s1, v254, 54
	v_mov_b32_e32 v48, s0
	s_addc_u32 s12, s1, 0
	s_lshl_b32 s13, s70, 7
	s_waitcnt lgkmcnt(0)
	s_barrier
	ds_read_b32 v48, v48
	s_add_u32 s78, s11, s13
	s_addc_u32 s79, s12, 0
	v_readlane_b32 s1, v254, 59
	s_add_u32 s10, s1, s10
	v_readlane_b32 s1, v254, 60
	s_addc_u32 s11, s1, 0
	s_add_u32 s80, s10, s13
	s_addc_u32 s81, s11, 0
	v_readlane_b32 s1, v255, 9
	v_lshlrev_b32_e32 v186, 1, v54
	s_bcnt1_i32_b32 s88, s6
	v_mov_b32_e32 v112, s1
	ds_read_b32 v112, v112
	s_waitcnt lgkmcnt(0)
	v_readfirstlane_b32 s10, v48
	v_readfirstlane_b32 s11, v112
	s_nop 1
	v_lshl_add_u32 v48, s10, 6, v212
	v_lshl_add_u32 v112, s11, 6, v212
	v_ashrrev_i32_e32 v49, 31, v48
	v_lshlrev_b64 v[48:49], 9, v[48:49]
	v_lshl_add_u64 v[50:51], s[78:79], 0, v[48:49]
	v_lshl_add_u64 v[50:51], v[50:51], 0, v[186:187]
	v_lshl_add_u64 v[48:49], s[80:81], 0, v[48:49]
	v_lshl_add_u64 v[48:49], v[48:49], 0, v[186:187]
	s_cmp_lt_u32 s88, 2
	s_cbranch_scc1 .Lslc_rot
	v_ashrrev_i32_e32 v113, 31, v112
	v_lshlrev_b64 v[112:113], 9, v[112:113]
	v_lshl_add_u64 v[50:51], s[78:79], 0, v[112:113]
	v_lshl_add_u64 v[48:49], s[80:81], 0, v[112:113]
	v_lshl_add_u64 v[50:51], v[50:51], 0, v[186:187]
	v_lshl_add_u64 v[48:49], v[48:49], 0, v[186:187]
	global_load_dwordx4 v[112:115], v[50:51], off
	global_load_dwordx4 v[116:119], v[48:49], off
.Lslc_rot:
	s_waitcnt vmcnt(6)
	v_and_b32_e32 v49, 0xffff0000, v44
	v_lshlrev_b32_e32 v48, 16, v44
	v_and_b32_e32 v51, 0xffff0000, v40
	v_lshlrev_b32_e32 v50, 16, v40
	v_pk_mul_f32 v[52:53], v[28:29], v[50:51]
	v_pk_mul_f32 v[28:29], v[28:29], v[48:49]
	v_pk_fma_f32 v[52:53], v[24:25], v[48:49], v[52:53] neg_lo:[0,0,1] neg_hi:[0,0,1]
	v_pk_fma_f32 v[24:25], v[24:25], v[50:51], v[28:29]
	v_and_b32_e32 v29, 0xffff0000, v45
	v_lshlrev_b32_e32 v28, 16, v45
	v_and_b32_e32 v45, 0xffff0000, v41
	v_lshlrev_b32_e32 v44, 16, v41
	v_pk_mul_f32 v[40:41], v[30:31], v[44:45]
	v_cvt_pk_bf16_f32 v160, v52, v53
	v_pk_fma_f32 v[40:41], v[26:27], v[28:29], v[40:41] neg_lo:[0,0,1] neg_hi:[0,0,1]
	v_pk_mul_f32 v[28:29], v[30:31], v[28:29]
	v_and_b32_e32 v31, 0xffff0000, v42
	v_lshlrev_b32_e32 v30, 16, v42
	v_pk_fma_f32 v[26:27], v[26:27], v[44:45], v[28:29]
	v_and_b32_e32 v29, 0xffff0000, v46
	v_lshlrev_b32_e32 v28, 16, v46
	v_pk_mul_f32 v[44:45], v[20:21], v[30:31]
	v_pk_mul_f32 v[20:21], v[20:21], v[28:29]
	v_pk_fma_f32 v[44:45], v[16:17], v[28:29], v[44:45] neg_lo:[0,0,1] neg_hi:[0,0,1]
	v_and_b32_e32 v29, 0xffff0000, v43
	v_lshlrev_b32_e32 v28, 16, v43
	v_pk_fma_f32 v[16:17], v[16:17], v[30:31], v[20:21]
	v_and_b32_e32 v21, 0xffff0000, v47
	v_lshlrev_b32_e32 v20, 16, v47
	v_pk_mul_f32 v[30:31], v[22:23], v[28:29]
	v_cvt_pk_bf16_f32 v166, v16, v17
	v_pk_fma_f32 v[30:31], v[18:19], v[20:21], v[30:31] neg_lo:[0,0,1] neg_hi:[0,0,1]
	v_pk_mul_f32 v[20:21], v[22:23], v[20:21]
	v_and_b32_e32 v17, 0xffff0000, v36
	v_pk_fma_f32 v[18:19], v[18:19], v[28:29], v[20:21]
	v_lshlrev_b32_e32 v16, 16, v36
	v_cvt_pk_bf16_f32 v167, v18, v19
	v_and_b32_e32 v19, 0xffff0000, v32
	v_lshlrev_b32_e32 v18, 16, v32
	v_pk_mul_f32 v[20:21], v[12:13], v[18:19]
	v_pk_mul_f32 v[12:13], v[12:13], v[16:17]
	v_pk_fma_f32 v[20:21], v[8:9], v[16:17], v[20:21] neg_lo:[0,0,1] neg_hi:[0,0,1]
	v_and_b32_e32 v17, 0xffff0000, v33
	v_lshlrev_b32_e32 v16, 16, v33
	v_pk_fma_f32 v[8:9], v[8:9], v[18:19], v[12:13]
	v_and_b32_e32 v13, 0xffff0000, v37
	v_lshlrev_b32_e32 v12, 16, v37
	v_pk_mul_f32 v[18:19], v[14:15], v[16:17]
	v_cvt_pk_bf16_f32 v161, v40, v41
	v_pk_fma_f32 v[18:19], v[10:11], v[12:13], v[18:19] neg_lo:[0,0,1] neg_hi:[0,0,1]
	v_pk_mul_f32 v[12:13], v[14:15], v[12:13]
	v_and_b32_e32 v15, 0xffff0000, v34
	v_lshlrev_b32_e32 v14, 16, v34
	v_pk_fma_f32 v[10:11], v[10:11], v[16:17], v[12:13]
	v_and_b32_e32 v13, 0xffff0000, v38
	v_lshlrev_b32_e32 v12, 16, v38
	v_pk_mul_f32 v[16:17], v[4:5], v[14:15]
	v_pk_mul_f32 v[4:5], v[4:5], v[12:13]
	v_pk_fma_f32 v[16:17], v[0:1], v[12:13], v[16:17] neg_lo:[0,0,1] neg_hi:[0,0,1]
	v_and_b32_e32 v13, 0xffff0000, v35
	v_lshlrev_b32_e32 v12, 16, v35
	v_pk_fma_f32 v[0:1], v[0:1], v[14:15], v[4:5]
	v_and_b32_e32 v5, 0xffff0000, v39
	v_lshlrev_b32_e32 v4, 16, v39
	v_pk_mul_f32 v[14:15], v[6:7], v[12:13]
	v_cvt_pk_bf16_f32 v162, v44, v45
	v_pk_fma_f32 v[14:15], v[2:3], v[4:5], v[14:15] neg_lo:[0,0,1] neg_hi:[0,0,1]
	v_pk_mul_f32 v[4:5], v[6:7], v[4:5]
	v_cvt_pk_bf16_f32 v163, v30, v31
	v_pk_fma_f32 v[2:3], v[2:3], v[12:13], v[4:5]
	v_cvt_pk_bf16_f32 v164, v24, v25
	v_cvt_pk_bf16_f32 v165, v26, v27
	v_cvt_pk_bf16_f32 v168, v20, v21
	v_cvt_pk_bf16_f32 v169, v18, v19
	v_cvt_pk_bf16_f32 v170, v16, v17
	v_cvt_pk_bf16_f32 v171, v14, v15
	v_cvt_pk_bf16_f32 v172, v8, v9
	v_cvt_pk_bf16_f32 v173, v10, v11
	v_cvt_pk_bf16_f32 v174, v0, v1
	v_cvt_pk_bf16_f32 v175, v2, v3
	s_cmp_lt_u32 s88, 2
	s_cbranch_scc1 .Lslc_pro_one
	s_waitcnt vmcnt(3)
	ds_write_b128 v215, v[128:131]
	s_waitcnt vmcnt(2)
	ds_write_b128 v215, v[132:135] offset:9216
	s_waitcnt vmcnt(1)
	ds_write_b128 v215, v[112:115] offset:18432
	s_waitcnt vmcnt(0)
	ds_write_b128 v215, v[116:119] offset:27648
	s_branch .LBB0_934

; #define NS_GLOAD(k_, KR, VR) do { const int jj = __builtin_amdgcn_readfirstlane(jl[(k_)]); KR = *(const u32x4*)(kg + (size_t)(64 * jj + sr) * pitch + sc * 8); VR = *(const u32x4*)(vg + (size_t)(64 * jj + sr) * pitch + sc * 8); } while (0)
; #define NS_LSTORE(st_, KR, VR) do { lds8* b = lds + (st_) * NS_STAGE; *(LAS u32x4*)(b + sr * NS_STR + sc * 16) = KR; *(LAS u32x4*)(b + 64 * NS_STR + sr * NS_STR + sc * 16) = VR; } while (0)
; template <int MODE>
; DI void nsa_branch(lds8* lds, const bf16_t* kg, const bf16_t* vg, int pitch, unsigned tiles, const bf16x8 (&q)[4], int qpos, unsigned mybits, int blk,
;                    f32x16 (&O)[2], float& muse, float& l, int tid, int lane, int grp, CmpCap& cap) {
;     ...
;   for (int d = 0; d < 2; ++d)
; #pragma unroll
;     for (int i = 0; i < 16; ++i) O[d][i] = 0.f;
;   muse = 0.f; l = 0.f;
;   u32x4 kra, vra;
;     ...
;   NS_GLOAD(0, kra, vra); NS_LSTORE(0, kra, vra);
;   if (ntl > 1) { NS_GLOAD(1, kra, vra); NS_LSTORE(1, kra, vra); }
;   __syncthreads();
;   f32x16 s0, s1, du0, du1; bf16x8 P[4];
;   int st_cur = 0;
.LBB0_934:
	v_lshl_add_u64 v[194:195], s[78:79], 0, v[186:187]
	s_cmp_eq_u32 s6, 0
	v_lshl_add_u64 v[196:197], s[80:81], 0, v[186:187]
	s_waitcnt lgkmcnt(0)
	s_barrier
	s_cbranch_scc1 .LBB0_968
	v_lshl_or_b32 v0, s77, 6, v214
	v_sub_u32_e32 v0, v211, v0
	s_mov_b32 s1, 0xefa18f08
	s_mov_b32 s2, s74
	s_mov_b64 s[4:5], s[72:73]
	s_mov_b32 s6, 0
	v_cmp_gt_i32_e64 s[10:11], 0, v0
	v_cmp_gt_i32_e64 s[12:13], 32, v0
	v_cmp_gt_i32_e64 s[14:15], 1, v0
	v_cmp_gt_i32_e64 s[16:17], 33, v0
	v_cmp_gt_i32_e64 s[18:19], 2, v0
	v_cmp_gt_i32_e64 s[20:21], 34, v0
	s_mov_b32 s89, 3
	v_cmp_gt_i32_e64 s[22:23], 3, v0
	v_cmp_gt_i32_e64 s[24:25], 35, v0
	v_cmp_gt_i32_e64 s[26:27], 8, v0
	v_cmp_gt_i32_e64 s[28:29], 40, v0
	v_cmp_gt_i32_e64 s[30:31], 9, v0
	v_cmp_gt_i32_e64 s[34:35], 41, v0
	v_cmp_gt_i32_e64 s[36:37], 10, v0
	v_cmp_gt_i32_e64 s[38:39], 42, v0
	v_cmp_gt_i32_e64 s[40:41], 11, v0
	v_cmp_gt_i32_e64 s[42:43], 43, v0
	v_cmp_gt_i32_e64 s[44:45], 16, v0
	v_cmp_gt_i32_e64 s[46:47], 48, v0
	v_cmp_gt_i32_e64 s[48:49], 17, v0
	v_cmp_gt_i32_e64 s[50:51], 49, v0
	v_cmp_gt_i32_e64 s[52:53], 18, v0
	v_cmp_gt_i32_e64 s[54:55], 50, v0
	v_cmp_gt_i32_e64 s[56:57], 19, v0
	v_cmp_gt_i32_e64 s[58:59], 51, v0
	v_cmp_gt_i32_e64 s[60:61], 24, v0
	v_cmp_gt_i32_e64 s[62:63], 56, v0
	v_cmp_gt_i32_e64 s[64:65], 25, v0
	v_cmp_gt_i32_e64 s[66:67], 57, v0
	v_cmp_gt_i32_e64 s[68:69], 26, v0
	v_cmp_gt_i32_e64 s[70:71], 58, v0
	v_cmp_gt_i32_e64 s[72:73], 27, v0
	v_cmp_gt_i32_e64 s[74:75], 59, v0
	s_add_i32 s90, 0, 0x16d10
	v_mov_b32_e32 v0, v187
	v_mov_b32_e32 v1, v187
	v_mov_b32_e32 v2, v187
	v_mov_b32_e32 v3, v187
	v_mov_b32_e32 v4, v187
	v_mov_b32_e32 v5, v187
	v_mov_b32_e32 v6, v187
	v_mov_b32_e32 v7, v187
	v_mov_b32_e32 v8, v187
	v_mov_b32_e32 v9, v187
	v_mov_b32_e32 v10, v187
	v_mov_b32_e32 v11, v187
	v_mov_b32_e32 v12, v187
	v_mov_b32_e32 v13, v187
	v_mov_b32_e32 v14, v187
	v_mov_b32_e32 v15, v187
	v_mov_b32_e32 v16, v187
	v_mov_b32_e32 v17, v187
	v_mov_b32_e32 v18, v187
	v_mov_b32_e32 v19, v187
	v_mov_b32_e32 v20, v187
	v_mov_b32_e32 v21, v187
	v_mov_b32_e32 v22, v187
	v_mov_b32_e32 v23, v187
	v_mov_b32_e32 v24, v187
	v_mov_b32_e32 v25, v187
	v_mov_b32_e32 v26, v187
	v_mov_b32_e32 v27, v187
	v_mov_b32_e32 v28, v187
	v_mov_b32_e32 v29, v187
	v_mov_b32_e32 v30, v187
	v_mov_b32_e32 v31, v187
	v_mov_b32_e32 v138, 0
	v_mov_b32_e32 v219, 0
	s_branch .LBB0_938

; #define NS_GLOAD(k_, KR, VR) do { const int jj = __builtin_amdgcn_readfirstlane(jl[(k_)]); KR = *(const u32x4*)(kg + (size_t)(64 * jj + sr) * pitch + sc * 8); VR = *(const u32x4*)(vg + (size_t)(64 * jj + sr) * pitch + sc * 8); } while (0)
; #define NS_LSTORE(st_, KR, VR) do { lds8* b = lds + (st_) * NS_STAGE; *(LAS u32x4*)(b + sr * NS_STR + sc * 16) = KR; *(LAS u32x4*)(b + 64 * NS_STR + sr * NS_STR + sc * 16) = VR; } while (0)
; template <int MODE>
; DI void nsa_branch(lds8* lds, const bf16_t* kg, const bf16_t* vg, int pitch, unsigned tiles, const bf16x8 (&q)[4], int qpos, unsigned mybits, int blk,
;                    f32x16 (&O)[2], float& muse, float& l, int tid, int lane, int grp, CmpCap& cap) {
;     ...
;   NS_GLOAD(0, kra, vra); NS_LSTORE(0, kra, vra);
;   if (ntl > 1) { NS_GLOAD(1, kra, vra); NS_LSTORE(1, kra, vra); }
;   __syncthreads();
; DI void nsa_unit(const Params& p, lds8* lds, int bl, int g, int qb32) {
;     ...
;   { const int jlo = blk >= 8 ? blk - 8 : 0; const unsigned wt = (blk == 31 ? 0xffffffffu : ((1u << (blk + 1)) - 1u)) & ~((1u << jlo) - 1u);
;     nsa_branch<2>(lds, KSW + rowbase * 256 + 128 + g * 64, VSW + rowbase * 256 + 128 + g * 64, 256, wt, qrot, qpos, 0u, blk, O, m, l, tid, lane, grp, cap); }
.LBB0_975:
	s_or_b64 exec, exec, s[10:11]
	v_mov_b32_e32 v32, s0
	v_readlane_b32 s1, v255, 9
	s_waitcnt lgkmcnt(0)
	s_barrier
	s_bcnt1_i32_b32 s3, s6
	s_waitcnt vmcnt(0)
	ds_write_b128 v215, v[236:239]
	ds_write_b128 v215, v[240:243] offset:9216
	s_cmp_lt_u32 s3, 2
	s_cbranch_scc1 .Lwin_pro_one
	ds_write_b128 v215, v[244:247] offset:18432
	ds_write_b128 v215, v[248:251] offset:27648
.Lwin_pro_one:
.LBB0_977:
	s_cmp_eq_u32 s6, 0
	s_waitcnt lgkmcnt(0)
	s_barrier
	s_cbranch_scc1 .LBB0_1011
	s_mov_b32 s6, 0
	v_mov_b32_e32 v32, v187
	v_mov_b32_e32 v33, v187
	v_mov_b32_e32 v34, v187
	v_mov_b32_e32 v35, v187
	v_mov_b32_e32 v36, v187
	v_mov_b32_e32 v37, v187
	v_mov_b32_e32 v38, v187
	v_mov_b32_e32 v39, v187
	v_mov_b32_e32 v40, v187
	v_mov_b32_e32 v41, v187
	v_mov_b32_e32 v42, v187
	v_mov_b32_e32 v43, v187
	v_mov_b32_e32 v44, v187
	v_mov_b32_e32 v45, v187
	v_mov_b32_e32 v46, v187
	v_mov_b32_e32 v47, v187
	v_mov_b32_e32 v48, v187
	v_mov_b32_e32 v49, v187
	v_mov_b32_e32 v50, v187
	v_mov_b32_e32 v51, v187
	v_mov_b32_e32 v52, v187
	v_mov_b32_e32 v53, v187
	v_mov_b32_e32 v54, v187
	v_mov_b32_e32 v55, v187
	v_mov_b32_e32 v56, v187
	v_mov_b32_e32 v57, v187
	v_mov_b32_e32 v58, v187
	v_mov_b32_e32 v59, v187
	v_mov_b32_e32 v60, v187
	v_mov_b32_e32 v61, v187
	v_mov_b32_e32 v62, v187
	v_mov_b32_e32 v63, v187
	v_mov_b32_e32 v221, 0
	s_mov_b32 s46, 3
	v_mov_b32_e32 v128, 0
	s_branch .LBB0_981
